# static s_setprio 1 for waves 4-7 (younger half) during the attention phase, reset after
# baseline (speedup 1.0000x reference)
.LBB0_1646:
	s_cmp_ge_u32 s97, 0x100
	s_cbranch_scc0 .Lattn_prio_skip
	s_setprio 1

.LBB0_1814:
	s_setprio 0
	s_cmp_lt_i32 s8, 15
	s_cselect_b64 s[4:5], -1, 0
	s_and_b64 s[6:7], s[4:5], s[2:3]
	s_andn2_b64 vcc, exec, s[6:7]
	s_cbranch_vccnz .LBB0_1857
	s_cmpk_lt_i32 s96, 0x400
	s_cselect_b64 s[2:3], -1, 0
	s_cmpk_gt_i32 s96, 0x3ff
	v_readfirstlane_b32 s14, v180
	s_cbranch_scc1 .LBB0_1821
	s_ashr_i32 s4, s96, 31
	s_lshr_b32 s4, s4, 29
	s_add_i32 s8, s96, s4
	s_and_b32 s4, s8, -8
	s_sub_i32 s9, s96, s4
	s_cmp_gt_i32 s9, -1
	s_cbranch_scc0 .LBB0_1818
	s_lshl_b32 s10, s9, 7
	s_cbranch_execz .LBB0_1819
	s_branch .LBB0_1820
